# v8 + nt hint on GEMM1 write-through (sc1) P/G stores
# speedup vs baseline: 1.0168x; 1.0168x over previous
; __device__ __forceinline__ unsigned cvtpk(float lo, float hi) { f32x2_t v = {lo, hi}; f16x2_t b = __builtin_convertvector(v, f16x2_t); return __builtin_bit_cast(unsigned, b); }
;     __device__ __forceinline__ void operator()(const f32x4 (&acc)[2][2][4][2], const Unit& u, int wr, int wc, int fr, int fq) const {
;     ...
; #pragma unroll
;         for (int ai = 0; ai < 2; ++ai)
; #pragma unroll
;             for (int m = 0; m < 4; ++m) { const int row = row0 + ai * HALF + m * 16; const int bl = row >> 12, t = row & 4095;
; #pragma unroll
;                 for (int bj = 0; bj < 2; ++bj) { const f32x4 v0 = acc[ai][bj][m][0] * rs[ai][m], v1 = acc[ai][bj][m][1] * rs[ai][m];
;                     u32x4 w; w.x = cvtpk(v0[0], v0[1]); w.y = cvtpk(v0[2], v0[3]); w.z = cvtpk(v1[0], v1[1]); w.w = cvtpk(v1[2], v1[3]);
;                     const int ct = bj * HALF + wc * 32 + 8 * fq;
;                     bf16_t* dst;
;                     if (pn < 18) { const int sect = pn / 6, hh = (pn - sect * 6) * 4 + (ct >> 6), dsh = 2 * (hh >> 3); const int idx = ((t & ((1 << dsh) - 1)) << (12 - dsh)) + (t >> dsh);
;                         dst = P + PL_A + ((size_t)((bl * 3 + sect) * 24 + hh) * 4096 + idx) * 64 + (ct & 63); }
;                     else if (pn < 22) { const int qk = (pn - 18) >> 1, head = ((pn - 18) & 1) * 2 + (ct >> 7);
;                         dst = P + PL_QR + (size_t)qk * PL_QK_SZ + ((size_t)(bl * 4 + head) * 4096 + t) * 128 + (ct & 127); }
;                     else if (pn < 30) { const int vg = (pn - 22) >> 2, head = (pn - 22) & 3;
;                         dst = P + PL_VR + (size_t)vg * PL_VG_SZ + ((size_t)(bl * 4 + head) * 4096 + t) * 256 + ct; }
;                     else dst = G + (size_t)row * 2048 + (pn - 30) * 256 + ct;
;                     *(u32x4*)dst = w; } }
.Lepi1_go:
	s_add_i32 s27, s55, s57
	s_waitcnt lgkmcnt(0)
	v_pk_mul_f32 v[126:127], v[126:127], v[150:151] op_sel_hi:[1,0]
	v_pk_mul_f32 v[128:129], v[128:129], v[150:151] op_sel_hi:[1,0]
	v_pk_mul_f32 v[122:123], v[122:123], v[150:151] op_sel_hi:[1,0]
	v_pk_mul_f32 v[124:125], v[124:125], v[150:151] op_sel_hi:[1,0]
	v_cvt_pk_f16_f32 v126, v126, v127
	v_cvt_pk_f16_f32 v127, v128, v129
	v_cvt_pk_f16_f32 v128, v122, v123
	v_cvt_pk_f16_f32 v129, v124, v125
	v_mov_b32_e32 v184, v183
	global_store_dwordx4 v184, v[126:129], s[100:101] sc1 nt
	v_pk_mul_f32 v[110:111], v[110:111], v[150:151] op_sel:[0,1] op_sel_hi:[1,1]
	v_pk_mul_f32 v[112:113], v[112:113], v[150:151] op_sel:[0,1] op_sel_hi:[1,1]
	v_pk_mul_f32 v[106:107], v[106:107], v[150:151] op_sel:[0,1] op_sel_hi:[1,1]
	v_pk_mul_f32 v[108:109], v[108:109], v[150:151] op_sel:[0,1] op_sel_hi:[1,1]
	v_cvt_pk_f16_f32 v110, v110, v111
	v_cvt_pk_f16_f32 v111, v112, v113
	v_cvt_pk_f16_f32 v112, v106, v107
	v_cvt_pk_f16_f32 v113, v108, v109
	v_add_u32_e32 v185, s45, v184
	global_store_dwordx4 v185, v[110:113], s[100:101] sc1 nt
	v_pk_mul_f32 v[94:95], v[94:95], v[148:149] op_sel_hi:[1,0]
	v_pk_mul_f32 v[96:97], v[96:97], v[148:149] op_sel_hi:[1,0]
	v_pk_mul_f32 v[90:91], v[90:91], v[148:149] op_sel_hi:[1,0]
	v_pk_mul_f32 v[92:93], v[92:93], v[148:149] op_sel_hi:[1,0]
	v_cvt_pk_f16_f32 v94, v94, v95
	v_cvt_pk_f16_f32 v95, v96, v97
	v_cvt_pk_f16_f32 v96, v90, v91
	v_cvt_pk_f16_f32 v97, v92, v93
	v_add_u32_e32 v186, s45, v185
	global_store_dwordx4 v186, v[94:97], s[100:101] sc1 nt
	v_pk_mul_f32 v[78:79], v[78:79], v[148:149] op_sel:[0,1] op_sel_hi:[1,1]
	v_pk_mul_f32 v[80:81], v[80:81], v[148:149] op_sel:[0,1] op_sel_hi:[1,1]
	v_pk_mul_f32 v[74:75], v[74:75], v[148:149] op_sel:[0,1] op_sel_hi:[1,1]
	v_pk_mul_f32 v[76:77], v[76:77], v[148:149] op_sel:[0,1] op_sel_hi:[1,1]
	v_cvt_pk_f16_f32 v78, v78, v79
	v_cvt_pk_f16_f32 v79, v80, v81
	v_cvt_pk_f16_f32 v80, v74, v75
	v_cvt_pk_f16_f32 v81, v76, v77
	v_add_u32_e32 v187, s45, v186
	global_store_dwordx4 v187, v[78:81], s[100:101] sc1 nt
	v_pk_mul_f32 v[118:119], v[118:119], v[150:151] op_sel_hi:[1,0]
	v_pk_mul_f32 v[120:121], v[120:121], v[150:151] op_sel_hi:[1,0]
	v_pk_mul_f32 v[114:115], v[114:115], v[150:151] op_sel_hi:[1,0]
	v_pk_mul_f32 v[116:117], v[116:117], v[150:151] op_sel_hi:[1,0]
	v_cvt_pk_f16_f32 v118, v118, v119
	v_cvt_pk_f16_f32 v119, v120, v121
	v_cvt_pk_f16_f32 v120, v114, v115
	v_cvt_pk_f16_f32 v121, v116, v117
	v_add_u32_e32 v184, s57, v183
	global_store_dwordx4 v184, v[118:121], s[100:101] sc1 nt
	v_pk_mul_f32 v[102:103], v[102:103], v[150:151] op_sel:[0,1] op_sel_hi:[1,1]
	v_pk_mul_f32 v[104:105], v[104:105], v[150:151] op_sel:[0,1] op_sel_hi:[1,1]
	v_pk_mul_f32 v[98:99], v[98:99], v[150:151] op_sel:[0,1] op_sel_hi:[1,1]
	v_pk_mul_f32 v[100:101], v[100:101], v[150:151] op_sel:[0,1] op_sel_hi:[1,1]
	v_cvt_pk_f16_f32 v102, v102, v103
	v_cvt_pk_f16_f32 v103, v104, v105
	v_cvt_pk_f16_f32 v104, v98, v99
	v_cvt_pk_f16_f32 v105, v100, v101
	v_add_u32_e32 v185, s45, v184
	global_store_dwordx4 v185, v[102:105], s[100:101] sc1 nt
	v_pk_mul_f32 v[86:87], v[86:87], v[148:149] op_sel_hi:[1,0]
	v_pk_mul_f32 v[88:89], v[88:89], v[148:149] op_sel_hi:[1,0]
	v_pk_mul_f32 v[82:83], v[82:83], v[148:149] op_sel_hi:[1,0]
	v_pk_mul_f32 v[84:85], v[84:85], v[148:149] op_sel_hi:[1,0]
	v_cvt_pk_f16_f32 v86, v86, v87
	v_cvt_pk_f16_f32 v87, v88, v89
	v_cvt_pk_f16_f32 v88, v82, v83
	v_cvt_pk_f16_f32 v89, v84, v85
	v_add_u32_e32 v186, s45, v185
	global_store_dwordx4 v186, v[86:89], s[100:101] sc1 nt
	v_pk_mul_f32 v[70:71], v[70:71], v[148:149] op_sel:[0,1] op_sel_hi:[1,1]
	v_pk_mul_f32 v[72:73], v[72:73], v[148:149] op_sel:[0,1] op_sel_hi:[1,1]
	v_pk_mul_f32 v[66:67], v[66:67], v[148:149] op_sel:[0,1] op_sel_hi:[1,1]
	v_pk_mul_f32 v[68:69], v[68:69], v[148:149] op_sel:[0,1] op_sel_hi:[1,1]
	v_cvt_pk_f16_f32 v70, v70, v71
	v_cvt_pk_f16_f32 v71, v72, v73
	v_cvt_pk_f16_f32 v72, v66, v67
	v_cvt_pk_f16_f32 v73, v68, v69
	v_add_u32_e32 v187, s45, v186
	global_store_dwordx4 v187, v[70:73], s[100:101] sc1 nt
	v_pk_mul_f32 v[62:63], v[62:63], v[146:147] op_sel_hi:[1,0]
	v_pk_mul_f32 v[64:65], v[64:65], v[146:147] op_sel_hi:[1,0]
	v_pk_mul_f32 v[58:59], v[58:59], v[146:147] op_sel_hi:[1,0]
; __device__ __forceinline__ unsigned cvtpk(float lo, float hi) { f32x2_t v = {lo, hi}; f16x2_t b = __builtin_convertvector(v, f16x2_t); return __builtin_bit_cast(unsigned, b); }
; #define PG8_BAR __builtin_amdgcn_s_barrier()
;     __device__ __forceinline__ void operator()(const f32x4 (&acc)[2][2][4][2], const Unit& u, int wr, int wc, int fr, int fq) const {
;     ...
;                 for (int bj = 0; bj < 2; ++bj) { const f32x4 v0 = acc[ai][bj][m][0] * rs[ai][m], v1 = acc[ai][bj][m][1] * rs[ai][m];
;                     u32x4 w; w.x = cvtpk(v0[0], v0[1]); w.y = cvtpk(v0[2], v0[3]); w.z = cvtpk(v1[0], v1[1]); w.w = cvtpk(v1[2], v1[3]);
;                     const int ct = bj * HALF + wc * 32 + 8 * fq;
;                     bf16_t* dst;
;                     if (pn < 18) { const int sect = pn / 6, hh = (pn - sect * 6) * 4 + (ct >> 6), dsh = 2 * (hh >> 3); const int idx = ((t & ((1 << dsh) - 1)) << (12 - dsh)) + (t >> dsh);
;                         dst = P + PL_A + ((size_t)((bl * 3 + sect) * 24 + hh) * 4096 + idx) * 64 + (ct & 63); }
;                     else if (pn < 22) { const int qk = (pn - 18) >> 1, head = ((pn - 18) & 1) * 2 + (ct >> 7);
;                         dst = P + PL_QR + (size_t)qk * PL_QK_SZ + ((size_t)(bl * 4 + head) * 4096 + t) * 128 + (ct & 127); }
;                     else if (pn < 30) { const int vg = (pn - 22) >> 2, head = (pn - 22) & 3;
;                         dst = P + PL_VR + (size_t)vg * PL_VG_SZ + ((size_t)(bl * 4 + head) * 4096 + t) * 256 + ct; }
;                     else dst = G + (size_t)row * 2048 + (pn - 30) * 256 + ct;
;                     *(u32x4*)dst = w; } }
; template <class Epi, class Sched, bool ALIGN_EPI = false, bool SP2 = false>
; __device__ __forceinline__ void gemm_phase(PG8_LAS unsigned char* lds, const Gemm g, const Sched& S, const Epi& E) {
;     ...
;         if (!has_next) break;
; #pragma unroll
;         for (int a = 0; a < 2; ++a)
; #pragma unroll
;             for (int b = 0; b < 2; ++b)
; #pragma unroll
;                 for (int m = 0; m < 4; ++m)
; #pragma unroll
;                     for (int n = 0; n < 2; ++n) acc[a][b][m][n] = (f32x4){0.f, 0.f, 0.f, 0.f};
;         cur = nxt; cA = nA; cB = nB; ++ui;
;         if constexpr (ALIGN_EPI) { if (wr == 1) PG8_BAR; }
	v_pk_mul_f32 v[60:61], v[60:61], v[146:147] op_sel_hi:[1,0]
	v_cvt_pk_f16_f32 v62, v62, v63
	v_cvt_pk_f16_f32 v63, v64, v65
	v_cvt_pk_f16_f32 v64, v58, v59
	v_cvt_pk_f16_f32 v65, v60, v61
	v_add_u32_e32 v184, s55, v183
	global_store_dwordx4 v184, v[62:65], s[100:101] sc1 nt
	v_pk_mul_f32 v[46:47], v[46:47], v[146:147] op_sel:[0,1] op_sel_hi:[1,1]
	v_pk_mul_f32 v[48:49], v[48:49], v[146:147] op_sel:[0,1] op_sel_hi:[1,1]
	v_pk_mul_f32 v[42:43], v[42:43], v[146:147] op_sel:[0,1] op_sel_hi:[1,1]
	v_pk_mul_f32 v[44:45], v[44:45], v[146:147] op_sel:[0,1] op_sel_hi:[1,1]
	v_cvt_pk_f16_f32 v46, v46, v47
	v_cvt_pk_f16_f32 v47, v48, v49
	v_cvt_pk_f16_f32 v48, v42, v43
	v_cvt_pk_f16_f32 v49, v44, v45
	v_add_u32_e32 v185, s45, v184
	global_store_dwordx4 v185, v[46:49], s[100:101] sc1 nt
	v_pk_mul_f32 v[30:31], v[30:31], v[142:143] op_sel_hi:[1,0]
	v_pk_mul_f32 v[32:33], v[32:33], v[142:143] op_sel_hi:[1,0]
	v_pk_mul_f32 v[26:27], v[26:27], v[142:143] op_sel_hi:[1,0]
	v_pk_mul_f32 v[28:29], v[28:29], v[142:143] op_sel_hi:[1,0]
	v_cvt_pk_f16_f32 v30, v30, v31
	v_cvt_pk_f16_f32 v31, v32, v33
	v_cvt_pk_f16_f32 v32, v26, v27
	v_cvt_pk_f16_f32 v33, v28, v29
	v_add_u32_e32 v186, s45, v185
	global_store_dwordx4 v186, v[30:33], s[100:101] sc1 nt
	v_pk_mul_f32 v[14:15], v[14:15], v[142:143] op_sel:[0,1] op_sel_hi:[1,1]
	v_pk_mul_f32 v[16:17], v[16:17], v[142:143] op_sel:[0,1] op_sel_hi:[1,1]
	v_pk_mul_f32 v[10:11], v[10:11], v[142:143] op_sel:[0,1] op_sel_hi:[1,1]
	v_pk_mul_f32 v[12:13], v[12:13], v[142:143] op_sel:[0,1] op_sel_hi:[1,1]
	v_cvt_pk_f16_f32 v14, v14, v15
	v_cvt_pk_f16_f32 v15, v16, v17
	v_cvt_pk_f16_f32 v16, v10, v11
	v_cvt_pk_f16_f32 v17, v12, v13
	v_add_u32_e32 v187, s45, v186
	global_store_dwordx4 v187, v[14:17], s[100:101] sc1 nt
	v_pk_mul_f32 v[54:55], v[54:55], v[146:147] op_sel_hi:[1,0]
	v_pk_mul_f32 v[56:57], v[56:57], v[146:147] op_sel_hi:[1,0]
	v_pk_mul_f32 v[50:51], v[50:51], v[146:147] op_sel_hi:[1,0]
	v_pk_mul_f32 v[52:53], v[52:53], v[146:147] op_sel_hi:[1,0]
	v_cvt_pk_f16_f32 v54, v54, v55
	v_cvt_pk_f16_f32 v55, v56, v57
	v_cvt_pk_f16_f32 v56, v50, v51
	v_cvt_pk_f16_f32 v57, v52, v53
	v_add_u32_e32 v184, s27, v183
	global_store_dwordx4 v184, v[54:57], s[100:101] sc1 nt
	v_pk_mul_f32 v[38:39], v[38:39], v[146:147] op_sel:[0,1] op_sel_hi:[1,1]
	v_pk_mul_f32 v[40:41], v[40:41], v[146:147] op_sel:[0,1] op_sel_hi:[1,1]
	v_pk_mul_f32 v[34:35], v[34:35], v[146:147] op_sel:[0,1] op_sel_hi:[1,1]
	v_pk_mul_f32 v[36:37], v[36:37], v[146:147] op_sel:[0,1] op_sel_hi:[1,1]
	v_cvt_pk_f16_f32 v38, v38, v39
	v_cvt_pk_f16_f32 v39, v40, v41
	v_cvt_pk_f16_f32 v40, v34, v35
	v_cvt_pk_f16_f32 v41, v36, v37
	v_add_u32_e32 v185, s45, v184
	global_store_dwordx4 v185, v[38:41], s[100:101] sc1 nt
	v_pk_mul_f32 v[22:23], v[22:23], v[142:143] op_sel_hi:[1,0]
	v_pk_mul_f32 v[24:25], v[24:25], v[142:143] op_sel_hi:[1,0]
	v_pk_mul_f32 v[18:19], v[18:19], v[142:143] op_sel_hi:[1,0]
	v_pk_mul_f32 v[20:21], v[20:21], v[142:143] op_sel_hi:[1,0]
	v_cvt_pk_f16_f32 v22, v22, v23
	v_cvt_pk_f16_f32 v23, v24, v25
	v_cvt_pk_f16_f32 v24, v18, v19
	v_cvt_pk_f16_f32 v25, v20, v21
	v_add_u32_e32 v186, s45, v185
	global_store_dwordx4 v186, v[22:25], s[100:101] sc1 nt
	v_pk_mul_f32 v[6:7], v[6:7], v[142:143] op_sel:[0,1] op_sel_hi:[1,1]
	v_pk_mul_f32 v[8:9], v[8:9], v[142:143] op_sel:[0,1] op_sel_hi:[1,1]
	v_pk_mul_f32 v[2:3], v[2:3], v[142:143] op_sel:[0,1] op_sel_hi:[1,1]
	v_pk_mul_f32 v[4:5], v[4:5], v[142:143] op_sel:[0,1] op_sel_hi:[1,1]
	v_cvt_pk_f16_f32 v6, v6, v7
	v_cvt_pk_f16_f32 v7, v8, v9
	v_cvt_pk_f16_f32 v8, v2, v3
	v_cvt_pk_f16_f32 v9, v4, v5
	v_add_u32_e32 v187, s45, v186
	global_store_dwordx4 v187, v[6:9], s[100:101] sc1 nt
	s_mov_b32 s30, 0x8000
	s_mov_b32 s31, s65
	v_readlane_b32 s76, v253, 5
	v_readlane_b32 s77, v253, 6
	v_readlane_b32 s78, v253, 7
	v_readlane_b32 s79, v253, 8
	s_movk_i32 s80, 0x4000
	s_movk_i32 s81, 0x1000
	v_readlane_b32 s84, v255, 30
	s_mov_b32 s85, 0x11000
	s_mov_b32 s70, 1
	s_andn2_b64 vcc, exec, s[38:39]
	s_mov_b64 s[24:25], -1
	s_mov_b32 s56, 0x21000
	s_cbranch_vccnz .LBB0_149
	v_readlane_b32 s24, v255, 49
	v_readlane_b32 s25, v255, 50
	s_andn2_b64 vcc, exec, s[24:25]
	s_cbranch_vccnz .LBB0_148
	s_barrier
	s_branch .LBB0_148
